# phase F: next tile row-rstd copied LDS to LDS when the row block repeats (gridDim multiple of 64) instead of reloading partial sums
# baseline (speedup 1.0000x reference)
; __device__ __forceinline__ int lane_fresh() { int l; asm volatile("v_mbcnt_lo_u32_b32 %0, -1, 0\n\tv_mbcnt_hi_u32_b32 %0, -1, %0" : "=v"(l)); return l; }
; #define ACC_ZERO(acc) do { _Pragma("unroll") for (int ai = 0; ai < 2; ++ai) _Pragma("unroll") for (int bj = 0; bj < 2; ++bj) \
;   _Pragma("unroll") for (int m = 0; m < 4; ++m) _Pragma("unroll") for (int n = 0; n < 2; ++n) acc[ai][bj][m][n] = (f32x4){0.f, 0.f, 0.f, 0.f}; } while (0)
; __device__ __forceinline__ void phaseF(const Params& p, const int wv, const int rep) {
;     ...
;     auto fill_rs = [&](int t, int buf) {
;       const int tid = wv * 64 + lane_fresh();
;       if (tid < 256) {
;         const float* ps = PS + (size_t)((t & 63) * 256 + tid) * 16;
;         f32x4 a = *(const f32x4*)ps + *(const f32x4*)(ps + 4) + *(const f32x4*)(ps + 8) + *(const f32x4*)(ps + 12);
;         rs_l[buf * 256 + tid] = rsqrtf((a[0] + a[1] + a[2] + a[3]) * (1.f / 1024.f) + EPS);
;       }
;     };
;     int t_ = blockIdx.x, it = 0;
;     const int tend = 1024 * rep;
;     Acc acc;
;     if (t_ < tend) {
;       const int t = t_ & 1023;
;       fill_rs(t, 0);
;       kloop_t<1, true>(H2B + (size_t)((t & 63) * 256) * 1024, 1024, WUP + (size_t)((t >> 6) * 256) * 1024, 1024, 1024, acc, wv);
;     }
;     while (t_ < tend) {
;       const int t = t_ & 1023;
;       const int pm = t & 63, pn = t >> 6, brow = pm * 256, bcol = pn * 256;
;       ACC_ZERO(acc);
;       kloop_t<2>(H2B + (size_t)brow * 1024, 1024, WUP + (size_t)bcol * 1024, 1024, 1024, acc, wv);
;       t_ += gridDim.x;
;       if (t_ < tend) {
;         const int tn = t_ & 1023;
;         fill_rs(tn, (it + 1) & 1);
;         kloop_t<1, false>(H2B + (size_t)((tn & 63) * 256) * 1024, 1024, WUP + (size_t)((tn >> 6) * 256) * 1024, 1024, 1024, acc, wv);
.LBB0_1072:
	v_readlane_b32 s36, v251, 1
	s_add_i32 s75, s75, s36
	s_cmp_ge_i32 s75, s45
	s_cselect_b64 s[36:37], -1, 0
	s_and_b64 vcc, exec, s[36:37]
	s_cbranch_vccnz .LBB0_1065
	v_mbcnt_lo_u32_b32 v128, -1, 0
	v_mbcnt_hi_u32_b32 v128, -1, v128
	s_and_b32 s40, s75, 0x3ff
	v_add_u32_e32 v128, s88, v128
	v_cmp_gt_i32_e32 vcc, s52, v128
	s_and_saveexec_b64 s[38:39], vcc
	s_cbranch_execz .LBB0_1064
	v_readlane_b32 s41, v251, 1
	s_and_b32 s41, s41, 63
	s_cmp_lg_u32 s41, 0
	s_cbranch_scc1 .Lfrs_slow
	s_lshl_b32 s41, s76, 10
	s_and_b32 s41, s41, 0x400
	s_add_i32 s41, s41, 16
	v_lshl_add_u32 v130, v128, 2, s41
	v_add_u32_e32 v130, 0x20000, v130
	ds_read_b32 v131, v130
	s_not_b32 s41, s76
	s_lshl_b32 s41, s41, 10
	s_and_b32 s41, s41, 0x400
	s_add_i32 s41, s41, 16
	v_lshl_add_u32 v128, v128, 2, s41
	v_add_u32_e32 v128, 0x20000, v128
	s_waitcnt lgkmcnt(0)
	ds_write_b32 v128, v131
	s_branch .LBB0_1064
.Lfrs_slow:
	s_lshl_b32 s41, s40, 8
	s_and_b32 s41, s41, 0x3f00
	v_add_u32_e32 v130, s41, v128
	v_ashrrev_i32_e32 v131, 31, v130
	v_lshlrev_b64 v[130:131], 6, v[130:131]
	v_lshl_add_u64 v[130:131], s[0:1], 0, v[130:131]
	global_load_dwordx4 v[134:137], v[130:131], off
	global_load_dwordx4 v[138:141], v[130:131], off offset:16
	global_load_dwordx4 v[142:145], v[130:131], off offset:32
	global_load_dwordx4 v[146:149], v[130:131], off offset:48
	s_not_b32 s41, s76
	s_lshl_b32 s41, s41, 10
	s_and_b32 s41, s41, 0x400
	s_add_i32 s41, s41, 16
	v_lshl_add_u32 v128, v128, 2, s41
	v_add_u32_e32 v128, 0x20000, v128
	s_waitcnt vmcnt(0)
	v_pk_add_f32 v[134:135], v[134:135], v[138:139]
	v_pk_add_f32 v[130:131], v[136:137], v[140:141]
	v_pk_add_f32 v[134:135], v[134:135], v[142:143]
	v_pk_add_f32 v[130:131], v[130:131], v[144:145]
	v_pk_add_f32 v[134:135], v[134:135], v[146:147]
	v_pk_add_f32 v[130:131], v[130:131], v[148:149]
	v_add_f32_e32 v134, v134, v135
	v_add_f32_e32 v130, v130, v134
	v_add_f32_e32 v130, v131, v130
	v_fmamk_f32 v130, v130, 0x3a800000, v133
	v_mul_f32_e32 v131, 0x4b800000, v130
	v_cmp_gt_f32_e32 vcc, s74, v130
	s_nop 1
	v_cndmask_b32_e32 v130, v130, v131, vcc
	v_rsq_f32_e32 v130, v130
	s_nop 0
	v_mul_f32_e32 v131, 0x45800000, v130
	v_cndmask_b32_e32 v130, v130, v131, vcc
	ds_write_b32 v128, v130
	s_branch .LBB0_1064
